# code placement: all three K-loops with the same burst/barrier byte phases (heads at 20 / 16 / 20 mod 64)
# baseline (speedup 1.0000x reference)
; #define PG8_STAGE(bufoff, gbase, voff) do { _Pragma("unroll") for (int _i = 0; _i < 2; ++_i) \
;         __builtin_amdgcn_global_load_lds((const unsigned*)((const char*)(gbase) + (voff)[_i]), (LAS unsigned*)(lds + (bufoff) + ldsw + _i * 8192), 16, 0, 0); } while (0)
; #define PG8_LDA(dst, b, h) do { _Pragma("unroll") for (int m = 0; m < 4; ++m) _Pragma("unroll") for (int k = 0; k < 2; ++k) dst[m][k] = *(const LAS bf16x8*)(lds + PG8_SA(b, h) + aoff + m * 2048 + k * 1024); } while (0)
; #define PG8_LDB(dst, b, h) do { _Pragma("unroll") for (int n = 0; n < 2; ++n) _Pragma("unroll") for (int k = 0; k < 2; ++k) dst[n][k] = *(const LAS bf16x8*)(lds + PG8_SB(b, h) + boff + n * 2048 + k * 1024); } while (0)
; #define PG8_MMA(ai, bj, At, Bt) do { __builtin_amdgcn_s_setprio(1); _Pragma("unroll") for (int m = 0; m < 4; ++m) _Pragma("unroll") for (int n = 0; n < 2; ++n) _Pragma("unroll") for (int k = 0; k < 2; ++k) \
;         acc[ai][bj][m][n] = __builtin_amdgcn_mfma_f32_16x16x32_bf16(Bt[n][k], At[m][k], acc[ai][bj][m][n], 0, 0, 0); __builtin_amdgcn_s_setprio(0); } while (0)
; #define PG8_WAIT_V(n) asm volatile("s_waitcnt vmcnt(" #n ")" ::: "memory")
; #define PG8_WAIT_L(n) asm volatile("s_waitcnt lgkmcnt(" #n ")" ::: "memory")
; #define PG8_BAR __builtin_amdgcn_s_barrier()
; #define PG8_SCHED __builtin_amdgcn_sched_barrier(0)
;     ...
;         const bool has_next = S.next(ui + 1, nxt);
;         const char* nA = has_next ? nxt.A : cA; const char* nB = has_next ? nxt.B : cB;
;         for (int t = 0; t < nt; t += 2) {
;             const bool last = (t == nt - 2);
;             const char* a1 = cA + (size_t)(t + 1) * kstep;
;             const char* a2 = last ? nA : cA + (size_t)(t + 2) * kstep; const char* b2 = last ? nB : cB + (size_t)(t + 2) * kstep;
;             const char* a3 = a2 + kstep; const char* b3 = b2 + kstep;
;             PG8_LDB(B0, 0, 0); PG8_LDB(B1, 0, 1); PG8_SCHED; PG8_LDA(At, 0, 0); PG8_STAGE(PG8_SA(1, 1), a1 + hstepA, voffA);
;             PG8_WAIT_V(8); PG8_WAIT_L(0); PG8_BAR; PG8_MMA(0, 0, At, B0); PG8_MMA(0, 1, At, B1); PG8_BAR; PG8_SCHED;
;             PG8_LDA(At, 0, 1); PG8_STAGE(PG8_SB(0, 0), b2, voffB); PG8_STAGE(PG8_SB(0, 1), b2 + hstepB, voffB); PG8_STAGE(PG8_SA(0, 0), a2, voffA);
;             PG8_WAIT_V(8); PG8_WAIT_L(0); PG8_BAR; PG8_MMA(1, 0, At, B0); PG8_MMA(1, 1, At, B1); PG8_BAR; PG8_SCHED;
.LBB0_415:
	s_mov_b64 s[12:13], s[18:19]
	v_mov_b32_e32 v150, v144
	s_xor_b64 s[18:19], s[16:17], -1
	v_mov_b32_e32 v144, s13
	s_mov_b64 s[68:69], s[2:3]
	s_and_b64 s[0:1], s[16:17], exec
	v_cndmask_b32_e64 v151, v129, v144, s[16:17]
	v_mov_b32_e32 v144, s12
	s_mov_b64 s[56:57], s[8:9]
	s_mov_b32 s62, s26
	s_cselect_b32 s6, s69, s53
	s_cselect_b32 s7, s68, s52
	v_cndmask_b32_e64 v152, v128, v144, s[16:17]
	s_mov_b32 s2, 0
	s_mov_b64 s[0:1], 0x100
	v_mov_b64_e32 v[144:145], v[142:143]
	v_mov_b64_e32 v[146:147], v[140:141]
	s_nop 0
	s_nop 0
.LBB0_416:
	s_add_i32 s8, s2, 2
	s_add_u32 s9, s52, s0
	s_addc_u32 s3, s53, s1
	s_add_i32 s26, 0, 0x10000
	s_cmp_eq_u32 s65, s2
	s_cselect_b32 s3, s6, s3
	s_cselect_b32 s2, s7, s9
	v_add_u32_e32 v153, s26, v148
	s_cselect_b64 vcc, -1, 0
	s_add_i32 s9, 0, 0x14000
	v_lshl_add_u64 v[170:171], v[128:129], 0, s[0:1]
	ds_read_b128 v[154:157], v153
	ds_read_b128 v[158:161], v153 offset:1024
	ds_read_b128 v[162:165], v153 offset:2048
	ds_read_b128 v[166:169], v153 offset:3072
	v_add_u32_e32 v153, s9, v148
	v_cndmask_b32_e32 v205, v171, v151, vcc
	v_cndmask_b32_e32 v204, v170, v152, vcc
	ds_read_b128 v[170:173], v153
	ds_read_b128 v[174:177], v153 offset:1024
	ds_read_b128 v[178:181], v153 offset:2048
	ds_read_b128 v[188:191], v153 offset:3072
	v_lshl_add_u64 v[244:245], s[52:53], 0, v[146:147]
	s_add_i32 m0, s41, 0xc000
	ds_read_b128 v[192:195], v149
	ds_read_b128 v[196:199], v149 offset:1024
	ds_read_b128 v[200:203], v149 offset:2048
	ds_read_b128 v[224:227], v149 offset:3072
	ds_read_b128 v[228:231], v149 offset:4096
	ds_read_b128 v[232:235], v149 offset:5120
	ds_read_b128 v[236:239], v149 offset:6144
	ds_read_b128 v[240:243], v149 offset:7168
	global_load_lds_dwordx4 v[244:245], off
	v_lshl_add_u64 v[244:245], s[52:53], 0, v[144:145]
	s_add_i32 m0, s41, 0xe000
	s_nop 0
	global_load_lds_dwordx4 v[244:245], off
	s_waitcnt vmcnt(8)
	s_waitcnt lgkmcnt(0)
	s_barrier
	s_setprio 1
	s_waitcnt lgkmcnt(0)
	v_mfma_f32_16x16x32_bf16 v[124:127], v[154:157], v[192:195], v[124:127]
	v_mfma_f32_16x16x32_bf16 v[120:123], v[162:165], v[192:195], v[120:123]
	v_mfma_f32_16x16x32_bf16 v[116:119], v[154:157], v[200:203], v[116:119]
	v_mfma_f32_16x16x32_bf16 v[112:115], v[162:165], v[200:203], v[112:115]
	v_mfma_f32_16x16x32_bf16 v[108:111], v[154:157], v[228:231], v[108:111]
	v_mfma_f32_16x16x32_bf16 v[104:107], v[162:165], v[228:231], v[104:107]
	v_mfma_f32_16x16x32_bf16 v[100:103], v[154:157], v[236:239], v[100:103]
	v_mfma_f32_16x16x32_bf16 v[96:99], v[162:165], v[236:239], v[96:99]
	v_mfma_f32_16x16x32_bf16 v[124:127], v[158:161], v[196:199], v[124:127]
	v_mfma_f32_16x16x32_bf16 v[120:123], v[166:169], v[196:199], v[120:123]
	v_mfma_f32_16x16x32_bf16 v[116:119], v[158:161], v[224:227], v[116:119]
	v_mfma_f32_16x16x32_bf16 v[112:115], v[166:169], v[224:227], v[112:115]
	v_mfma_f32_16x16x32_bf16 v[108:111], v[158:161], v[232:235], v[108:111]
	v_mfma_f32_16x16x32_bf16 v[104:107], v[166:169], v[232:235], v[104:107]
	v_mfma_f32_16x16x32_bf16 v[100:103], v[158:161], v[240:243], v[100:103]
	v_mfma_f32_16x16x32_bf16 v[96:99], v[166:169], v[240:243], v[96:99]
	s_setprio 0
	s_setprio 1
	v_mfma_f32_16x16x32_bf16 v[92:95], v[170:173], v[192:195], v[92:95]
	v_mfma_f32_16x16x32_bf16 v[88:91], v[178:181], v[192:195], v[88:91]
	v_mfma_f32_16x16x32_bf16 v[84:87], v[170:173], v[200:203], v[84:87]
	v_mfma_f32_16x16x32_bf16 v[80:83], v[178:181], v[200:203], v[80:83]
	v_mfma_f32_16x16x32_bf16 v[76:79], v[170:173], v[228:231], v[76:79]
	v_mfma_f32_16x16x32_bf16 v[72:75], v[178:181], v[228:231], v[72:75]
	v_mfma_f32_16x16x32_bf16 v[68:71], v[170:173], v[236:239], v[68:71]
	v_mfma_f32_16x16x32_bf16 v[64:67], v[178:181], v[236:239], v[64:67]
	v_mfma_f32_16x16x32_bf16 v[92:95], v[174:177], v[196:199], v[92:95]
	v_mfma_f32_16x16x32_bf16 v[88:91], v[188:191], v[196:199], v[88:91]
	v_mfma_f32_16x16x32_bf16 v[84:87], v[174:177], v[224:227], v[84:87]
	v_mfma_f32_16x16x32_bf16 v[80:83], v[188:191], v[224:227], v[80:83]
	v_mfma_f32_16x16x32_bf16 v[76:79], v[174:177], v[232:235], v[76:79]
	v_mfma_f32_16x16x32_bf16 v[72:75], v[188:191], v[232:235], v[72:75]
	v_mfma_f32_16x16x32_bf16 v[68:71], v[174:177], v[240:243], v[68:71]
	v_mfma_f32_16x16x32_bf16 v[64:67], v[188:191], v[240:243], v[64:67]
	s_setprio 0
	s_barrier
	s_add_i32 s26, s26, s40
	v_lshl_add_u64 v[244:245], v[204:205], 0, v[132:133]
	s_mov_b32 m0, s26
	ds_read_b128 v[192:195], v149 offset:16384
	ds_read_b128 v[196:199], v149 offset:17408
	ds_read_b128 v[200:203], v149 offset:18432
	ds_read_b128 v[224:227], v149 offset:19456
	ds_read_b128 v[228:231], v149 offset:20480
	ds_read_b128 v[232:235], v149 offset:21504
	ds_read_b128 v[236:239], v149 offset:22528
	ds_read_b128 v[240:243], v149 offset:23552
	global_load_lds_dwordx4 v[244:245], off
	v_lshl_add_u64 v[246:247], v[204:205], 0, v[136:137]
	s_add_i32 m0, s26, 0x2000
	v_lshl_add_u64 v[204:205], v[204:205], 0, s[58:59]
	s_add_i32 s9, s9, s40
	global_load_lds_dwordx4 v[246:247], off
	v_lshl_add_u64 v[248:249], v[204:205], 0, v[132:133]
	s_mov_b32 m0, s9
	v_lshl_add_u64 v[204:205], v[204:205], 0, v[136:137]
	global_load_lds_dwordx4 v[248:249], off
	s_add_i32 m0, s9, 0x2000
	v_lshl_add_u64 v[250:251], s[2:3], 0, v[130:131]
	global_load_lds_dwordx4 v[204:205], off
	s_mov_b32 m0, s41
	v_lshl_add_u64 v[218:219], s[2:3], 0, v[134:135]
	global_load_lds_dwordx4 v[250:251], off
	s_mov_b32 m0, s49
	s_nop 0
	global_load_lds_dwordx4 v[218:219], off
	s_waitcnt vmcnt(8)
	s_waitcnt lgkmcnt(0)
	s_barrier
; #define PG8_STAGE(bufoff, gbase, voff) do { _Pragma("unroll") for (int _i = 0; _i < 2; ++_i) \
;         __builtin_amdgcn_global_load_lds((const unsigned*)((const char*)(gbase) + (voff)[_i]), (LAS unsigned*)(lds + (bufoff) + ldsw + _i * 8192), 16, 0, 0); } while (0)
; #define PG8_LDA(dst, b, h) do { _Pragma("unroll") for (int m = 0; m < 4; ++m) _Pragma("unroll") for (int k = 0; k < 2; ++k) dst[m][k] = *(const LAS bf16x8*)(lds + PG8_SA(b, h) + aoff + m * 2048 + k * 1024); } while (0)
; #define PG8_LDB(dst, b, h) do { _Pragma("unroll") for (int n = 0; n < 2; ++n) _Pragma("unroll") for (int k = 0; k < 2; ++k) dst[n][k] = *(const LAS bf16x8*)(lds + PG8_SB(b, h) + boff + n * 2048 + k * 1024); } while (0)
; #define PG8_MMA(ai, bj, At, Bt) do { __builtin_amdgcn_s_setprio(1); _Pragma("unroll") for (int m = 0; m < 4; ++m) _Pragma("unroll") for (int n = 0; n < 2; ++n) _Pragma("unroll") for (int k = 0; k < 2; ++k) \
;         acc[ai][bj][m][n] = __builtin_amdgcn_mfma_f32_16x16x32_bf16(Bt[n][k], At[m][k], acc[ai][bj][m][n], 0, 0, 0); __builtin_amdgcn_s_setprio(0); } while (0)
; #define PG8_WAIT_V(n) asm volatile("s_waitcnt vmcnt(" #n ")" ::: "memory")
; #define PG8_WAIT_L(n) asm volatile("s_waitcnt lgkmcnt(" #n ")" ::: "memory")
; #define PG8_BAR __builtin_amdgcn_s_barrier()
; #define PG8_SCHED __builtin_amdgcn_sched_barrier(0)
;     ...
;             PG8_WAIT_V(8); PG8_WAIT_L(0); PG8_BAR; PG8_MMA(1, 0, At, B0); PG8_MMA(1, 1, At, B1); PG8_BAR; PG8_SCHED;
;             PG8_LDB(B0, 1, 0); PG8_LDB(B1, 1, 1); PG8_SCHED; PG8_LDA(At, 1, 0); PG8_STAGE(PG8_SA(0, 1), a2 + hstepA, voffA);
;             PG8_WAIT_V(8); PG8_WAIT_L(0); PG8_BAR; PG8_MMA(0, 0, At, B0); PG8_MMA(0, 1, At, B1); PG8_BAR; PG8_SCHED;
	s_setprio 1
	s_waitcnt lgkmcnt(0)
	v_mfma_f32_16x16x32_bf16 v[60:63], v[154:157], v[192:195], v[60:63]
	v_mfma_f32_16x16x32_bf16 v[56:59], v[162:165], v[192:195], v[56:59]
	v_mfma_f32_16x16x32_bf16 v[52:55], v[154:157], v[200:203], v[52:55]
	v_mfma_f32_16x16x32_bf16 v[48:51], v[162:165], v[200:203], v[48:51]
	v_mfma_f32_16x16x32_bf16 v[44:47], v[154:157], v[228:231], v[44:47]
	v_mfma_f32_16x16x32_bf16 v[40:43], v[162:165], v[228:231], v[40:43]
	v_mfma_f32_16x16x32_bf16 v[36:39], v[154:157], v[236:239], v[36:39]
	v_mfma_f32_16x16x32_bf16 v[32:35], v[162:165], v[236:239], v[32:35]
	v_mfma_f32_16x16x32_bf16 v[60:63], v[158:161], v[196:199], v[60:63]
	v_mfma_f32_16x16x32_bf16 v[56:59], v[166:169], v[196:199], v[56:59]
	v_mfma_f32_16x16x32_bf16 v[52:55], v[158:161], v[224:227], v[52:55]
	v_mfma_f32_16x16x32_bf16 v[48:51], v[166:169], v[224:227], v[48:51]
	v_mfma_f32_16x16x32_bf16 v[44:47], v[158:161], v[232:235], v[44:47]
	v_mfma_f32_16x16x32_bf16 v[40:43], v[166:169], v[232:235], v[40:43]
	v_mfma_f32_16x16x32_bf16 v[36:39], v[158:161], v[240:243], v[36:39]
	v_mfma_f32_16x16x32_bf16 v[32:35], v[166:169], v[240:243], v[32:35]
	s_setprio 0
	s_setprio 1
	v_mfma_f32_16x16x32_bf16 v[28:31], v[170:173], v[192:195], v[28:31]
	v_mfma_f32_16x16x32_bf16 v[24:27], v[178:181], v[192:195], v[24:27]
	v_mfma_f32_16x16x32_bf16 v[20:23], v[170:173], v[200:203], v[20:23]
	v_mfma_f32_16x16x32_bf16 v[16:19], v[178:181], v[200:203], v[16:19]
	v_mfma_f32_16x16x32_bf16 v[12:15], v[170:173], v[228:231], v[12:15]
	v_mfma_f32_16x16x32_bf16 v[8:11], v[178:181], v[228:231], v[8:11]
	v_mfma_f32_16x16x32_bf16 v[4:7], v[170:173], v[236:239], v[4:7]
	v_mfma_f32_16x16x32_bf16 v[0:3], v[178:181], v[236:239], v[0:3]
	v_mfma_f32_16x16x32_bf16 v[28:31], v[174:177], v[196:199], v[28:31]
	v_mfma_f32_16x16x32_bf16 v[24:27], v[188:191], v[196:199], v[24:27]
	v_mfma_f32_16x16x32_bf16 v[20:23], v[174:177], v[224:227], v[20:23]
	v_mfma_f32_16x16x32_bf16 v[16:19], v[188:191], v[224:227], v[16:19]
	v_mfma_f32_16x16x32_bf16 v[12:15], v[174:177], v[232:235], v[12:15]
	v_mfma_f32_16x16x32_bf16 v[8:11], v[188:191], v[232:235], v[8:11]
	v_mfma_f32_16x16x32_bf16 v[4:7], v[174:177], v[240:243], v[4:7]
	v_mfma_f32_16x16x32_bf16 v[0:3], v[188:191], v[240:243], v[0:3]
	s_setprio 0
	s_barrier
	s_add_i32 s9, 0, 0x18000
	v_add_u32_e32 v153, s9, v148
	s_add_i32 s26, 0, 0x1c000
	ds_read_b128 v[154:157], v153
	ds_read_b128 v[158:161], v153 offset:1024
	ds_read_b128 v[162:165], v153 offset:2048
	ds_read_b128 v[166:169], v153 offset:3072
	v_add_u32_e32 v153, s26, v148
	ds_read_b128 v[170:173], v153
	ds_read_b128 v[174:177], v153 offset:1024
	ds_read_b128 v[178:181], v153 offset:2048
	ds_read_b128 v[188:191], v153 offset:3072
	s_add_u32 s2, s2, s58
	s_addc_u32 s3, s3, 0
	s_mov_b32 m0, s10
	v_lshl_add_u64 v[212:213], s[2:3], 0, v[130:131]
	ds_read_b128 v[192:195], v149 offset:32768
	ds_read_b128 v[196:199], v149 offset:33792
	ds_read_b128 v[200:203], v149 offset:34816
	ds_read_b128 v[224:227], v149 offset:35840
	ds_read_b128 v[228:231], v149 offset:36864
	ds_read_b128 v[232:235], v149 offset:37888
	ds_read_b128 v[236:239], v149 offset:38912
	ds_read_b128 v[240:243], v149 offset:39936
	global_load_lds_dwordx4 v[212:213], off
	v_lshl_add_u64 v[212:213], s[2:3], 0, v[134:135]
	s_mov_b32 m0, s11
	s_nop 0
	global_load_lds_dwordx4 v[212:213], off
	s_waitcnt vmcnt(8)
	s_waitcnt lgkmcnt(0)
	s_barrier
	s_setprio 1
	s_waitcnt lgkmcnt(0)
	v_mfma_f32_16x16x32_bf16 v[124:127], v[154:157], v[192:195], v[124:127]
	v_mfma_f32_16x16x32_bf16 v[120:123], v[162:165], v[192:195], v[120:123]
	v_mfma_f32_16x16x32_bf16 v[116:119], v[154:157], v[200:203], v[116:119]
	v_mfma_f32_16x16x32_bf16 v[112:115], v[162:165], v[200:203], v[112:115]
	v_mfma_f32_16x16x32_bf16 v[108:111], v[154:157], v[228:231], v[108:111]
	v_mfma_f32_16x16x32_bf16 v[104:107], v[162:165], v[228:231], v[104:107]
	v_mfma_f32_16x16x32_bf16 v[100:103], v[154:157], v[236:239], v[100:103]
	v_mfma_f32_16x16x32_bf16 v[96:99], v[162:165], v[236:239], v[96:99]
	v_mfma_f32_16x16x32_bf16 v[124:127], v[158:161], v[196:199], v[124:127]
	v_mfma_f32_16x16x32_bf16 v[120:123], v[166:169], v[196:199], v[120:123]
	v_mfma_f32_16x16x32_bf16 v[116:119], v[158:161], v[224:227], v[116:119]
	v_mfma_f32_16x16x32_bf16 v[112:115], v[166:169], v[224:227], v[112:115]
	v_mfma_f32_16x16x32_bf16 v[108:111], v[158:161], v[232:235], v[108:111]
	v_mfma_f32_16x16x32_bf16 v[104:107], v[166:169], v[232:235], v[104:107]
	v_mfma_f32_16x16x32_bf16 v[100:103], v[158:161], v[240:243], v[100:103]
	v_mfma_f32_16x16x32_bf16 v[96:99], v[166:169], v[240:243], v[96:99]
	s_setprio 0
	s_setprio 1
	v_mfma_f32_16x16x32_bf16 v[92:95], v[170:173], v[192:195], v[92:95]
	v_mfma_f32_16x16x32_bf16 v[88:91], v[178:181], v[192:195], v[88:91]
	v_mfma_f32_16x16x32_bf16 v[84:87], v[170:173], v[200:203], v[84:87]
	v_mfma_f32_16x16x32_bf16 v[80:83], v[178:181], v[200:203], v[80:83]
	v_mfma_f32_16x16x32_bf16 v[76:79], v[170:173], v[228:231], v[76:79]
	v_mfma_f32_16x16x32_bf16 v[72:75], v[178:181], v[228:231], v[72:75]
	v_mfma_f32_16x16x32_bf16 v[68:71], v[170:173], v[236:239], v[68:71]
	v_mfma_f32_16x16x32_bf16 v[64:67], v[178:181], v[236:239], v[64:67]
	v_mfma_f32_16x16x32_bf16 v[92:95], v[174:177], v[196:199], v[92:95]
	v_mfma_f32_16x16x32_bf16 v[88:91], v[188:191], v[196:199], v[88:91]
	v_mfma_f32_16x16x32_bf16 v[84:87], v[174:177], v[224:227], v[84:87]
	v_mfma_f32_16x16x32_bf16 v[80:83], v[188:191], v[224:227], v[80:83]
	v_mfma_f32_16x16x32_bf16 v[76:79], v[174:177], v[232:235], v[76:79]
	v_mfma_f32_16x16x32_bf16 v[72:75], v[188:191], v[232:235], v[72:75]
	v_mfma_f32_16x16x32_bf16 v[68:71], v[174:177], v[240:243], v[68:71]
	v_mfma_f32_16x16x32_bf16 v[64:67], v[188:191], v[240:243], v[64:67]
	s_setprio 0
	s_barrier
; #define PG8_STAGE(bufoff, gbase, voff) do { _Pragma("unroll") for (int _i = 0; _i < 2; ++_i) \
;         __builtin_amdgcn_global_load_lds((const unsigned*)((const char*)(gbase) + (voff)[_i]), (LAS unsigned*)(lds + (bufoff) + ldsw + _i * 8192), 16, 0, 0); } while (0)
; #define PG8_LDA(dst, b, h) do { _Pragma("unroll") for (int m = 0; m < 4; ++m) _Pragma("unroll") for (int k = 0; k < 2; ++k) dst[m][k] = *(const LAS bf16x8*)(lds + PG8_SA(b, h) + aoff + m * 2048 + k * 1024); } while (0)
; #define PG8_MMA(ai, bj, At, Bt) do { __builtin_amdgcn_s_setprio(1); _Pragma("unroll") for (int m = 0; m < 4; ++m) _Pragma("unroll") for (int n = 0; n < 2; ++n) _Pragma("unroll") for (int k = 0; k < 2; ++k) \
;         acc[ai][bj][m][n] = __builtin_amdgcn_mfma_f32_16x16x32_bf16(Bt[n][k], At[m][k], acc[ai][bj][m][n], 0, 0, 0); __builtin_amdgcn_s_setprio(0); } while (0)
; #define PG8_WAIT_V(n) asm volatile("s_waitcnt vmcnt(" #n ")" ::: "memory")
; #define PG8_WAIT_L(n) asm volatile("s_waitcnt lgkmcnt(" #n ")" ::: "memory")
; #define PG8_BAR __builtin_amdgcn_s_barrier()
; #define PG8_SCHED __builtin_amdgcn_sched_barrier(0)
;     ...
;             PG8_WAIT_V(8); PG8_WAIT_L(0); PG8_BAR; PG8_MMA(0, 0, At, B0); PG8_MMA(0, 1, At, B1); PG8_BAR; PG8_SCHED;
;             PG8_LDA(At, 1, 1); PG8_STAGE(PG8_SB(1, 0), b3, voffB); PG8_STAGE(PG8_SB(1, 1), b3 + hstepB, voffB); PG8_STAGE(PG8_SA(1, 0), a3, voffA);
;             PG8_WAIT_V(8); PG8_WAIT_L(0); PG8_BAR; PG8_MMA(1, 0, At, B0); PG8_MMA(1, 1, At, B1); PG8_BAR; PG8_SCHED;
;         }
;         if (wr == 0) PG8_BAR;
	s_add_i32 s2, s9, s40
	v_lshl_add_u64 v[212:213], v[244:245], 0, s[70:71]
	s_mov_b32 m0, s2
	ds_read_b128 v[192:195], v149 offset:49152
	ds_read_b128 v[196:199], v149 offset:50176
	ds_read_b128 v[200:203], v149 offset:51200
	ds_read_b128 v[224:227], v149 offset:52224
	ds_read_b128 v[228:231], v149 offset:53248
	ds_read_b128 v[232:235], v149 offset:54272
	ds_read_b128 v[236:239], v149 offset:55296
	ds_read_b128 v[240:243], v149 offset:56320
	global_load_lds_dwordx4 v[212:213], off
	v_lshl_add_u64 v[212:213], v[246:247], 0, s[70:71]
	s_add_i32 m0, s2, 0x2000
	s_add_i32 s2, s26, s40
	global_load_lds_dwordx4 v[212:213], off
	v_lshl_add_u64 v[212:213], v[248:249], 0, s[70:71]
	s_mov_b32 m0, s2
	v_lshl_add_u64 v[204:205], v[204:205], 0, s[70:71]
	global_load_lds_dwordx4 v[212:213], off
	s_add_i32 m0, s2, 0x2000
	s_nop 0
	global_load_lds_dwordx4 v[204:205], off
	v_lshl_add_u64 v[204:205], v[250:251], 0, s[70:71]
	s_mov_b32 m0, s51
	s_nop 0
	global_load_lds_dwordx4 v[204:205], off
	v_lshl_add_u64 v[204:205], v[218:219], 0, s[70:71]
	s_mov_b32 m0, s64
	s_nop 0
	global_load_lds_dwordx4 v[204:205], off
	s_waitcnt vmcnt(8)
	s_waitcnt lgkmcnt(0)
	s_barrier
	s_setprio 1
	s_waitcnt lgkmcnt(0)
	v_mfma_f32_16x16x32_bf16 v[60:63], v[154:157], v[192:195], v[60:63]
	v_mfma_f32_16x16x32_bf16 v[56:59], v[162:165], v[192:195], v[56:59]
	v_mfma_f32_16x16x32_bf16 v[52:55], v[154:157], v[200:203], v[52:55]
	v_mfma_f32_16x16x32_bf16 v[48:51], v[162:165], v[200:203], v[48:51]
	v_mfma_f32_16x16x32_bf16 v[44:47], v[154:157], v[228:231], v[44:47]
	v_mfma_f32_16x16x32_bf16 v[40:43], v[162:165], v[228:231], v[40:43]
	v_mfma_f32_16x16x32_bf16 v[36:39], v[154:157], v[236:239], v[36:39]
	v_mfma_f32_16x16x32_bf16 v[32:35], v[162:165], v[236:239], v[32:35]
	v_mfma_f32_16x16x32_bf16 v[60:63], v[158:161], v[196:199], v[60:63]
	v_mfma_f32_16x16x32_bf16 v[56:59], v[166:169], v[196:199], v[56:59]
	v_mfma_f32_16x16x32_bf16 v[52:55], v[158:161], v[224:227], v[52:55]
	v_mfma_f32_16x16x32_bf16 v[48:51], v[166:169], v[224:227], v[48:51]
	v_mfma_f32_16x16x32_bf16 v[44:47], v[158:161], v[232:235], v[44:47]
	v_mfma_f32_16x16x32_bf16 v[40:43], v[166:169], v[232:235], v[40:43]
	v_mfma_f32_16x16x32_bf16 v[36:39], v[158:161], v[240:243], v[36:39]
	v_mfma_f32_16x16x32_bf16 v[32:35], v[166:169], v[240:243], v[32:35]
	s_setprio 0
	s_setprio 1
	v_mfma_f32_16x16x32_bf16 v[28:31], v[170:173], v[192:195], v[28:31]
	v_mfma_f32_16x16x32_bf16 v[24:27], v[178:181], v[192:195], v[24:27]
	v_mfma_f32_16x16x32_bf16 v[20:23], v[170:173], v[200:203], v[20:23]
	v_mfma_f32_16x16x32_bf16 v[16:19], v[178:181], v[200:203], v[16:19]
	v_mfma_f32_16x16x32_bf16 v[12:15], v[170:173], v[228:231], v[12:15]
	v_mfma_f32_16x16x32_bf16 v[8:11], v[178:181], v[228:231], v[8:11]
	v_mfma_f32_16x16x32_bf16 v[4:7], v[170:173], v[236:239], v[4:7]
	v_mfma_f32_16x16x32_bf16 v[0:3], v[178:181], v[236:239], v[0:3]
	v_mfma_f32_16x16x32_bf16 v[28:31], v[174:177], v[196:199], v[28:31]
	v_mfma_f32_16x16x32_bf16 v[24:27], v[188:191], v[196:199], v[24:27]
	v_mfma_f32_16x16x32_bf16 v[20:23], v[174:177], v[224:227], v[20:23]
	v_mfma_f32_16x16x32_bf16 v[16:19], v[188:191], v[224:227], v[16:19]
	v_mfma_f32_16x16x32_bf16 v[12:15], v[174:177], v[232:235], v[12:15]
	v_mfma_f32_16x16x32_bf16 v[8:11], v[188:191], v[232:235], v[8:11]
	v_mfma_f32_16x16x32_bf16 v[4:7], v[174:177], v[240:243], v[4:7]
	v_mfma_f32_16x16x32_bf16 v[0:3], v[188:191], v[240:243], v[0:3]
	s_setprio 0
	s_barrier
	s_add_u32 s0, s0, 0x100
	s_addc_u32 s1, s1, 0
	v_lshl_add_u64 v[146:147], v[146:147], 0, s[94:95]
	v_lshl_add_u64 v[144:145], v[144:145], 0, s[94:95]
	s_cmp_ge_u32 s8, s48
	s_mov_b32 s2, s8
	s_cbranch_scc0 .LBB0_416
	v_readlane_b32 s0, v254, 45
	v_readlane_b32 s1, v254, 46
	s_and_b64 vcc, exec, s[0:1]
	s_cbranch_vccz .LBB0_419
	s_barrier
